# sample-attention tile loop: the key-group LDS spin polls without s_sleep
# speedup vs baseline: 1.0006x; 1.0006x over previous
; #define LAS __attribute__((address_space(3)))
; __device__ __forceinline__ void group_sync(LAS unsigned* cnt, unsigned target, int lane) {
;     asm volatile("s_waitcnt lgkmcnt(0)" ::: "memory");
;     if (lane == 0) __hip_atomic_fetch_add(cnt, 1u, __ATOMIC_RELAXED, __HIP_MEMORY_SCOPE_WORKGROUP);
;     unsigned spins = 0;
;     while (__hip_atomic_load(cnt, __ATOMIC_RELAXED, __HIP_MEMORY_SCOPE_WORKGROUP) < target) { __builtin_amdgcn_s_sleep(1); if (++spins > (1u << 22)) break; }
;     asm volatile("" ::: "memory");
; }
.LBB0_1048:
	s_add_i32 s26, s29, 0
	s_add_i32 s26, s26, 0x20200
	v_mov_b32_e32 v2, s26
	ds_read_b32 v2, v2
	s_mov_b64 s[50:51], -1
	s_waitcnt lgkmcnt(0)
	v_cmp_le_u32_e32 vcc, s14, v2
	s_cbranch_vccnz .LBB0_1047
	v_mov_b32_e32 v2, s26
	s_nop 0
	ds_read_b32 v2, v2
	s_waitcnt lgkmcnt(0)
	v_cmp_gt_u32_e32 vcc, s14, v2
	s_cbranch_vccz .LBB0_1047
	v_mov_b32_e32 v2, s26
	s_nop 0
	ds_read_b32 v2, v2
	s_waitcnt lgkmcnt(0)
	v_cmp_gt_u32_e32 vcc, s14, v2
	s_cbranch_vccz .LBB0_1047
	v_mov_b32_e32 v2, s26
	s_nop 0
	ds_read_b32 v2, v2
	s_waitcnt lgkmcnt(0)
	v_cmp_gt_u32_e32 vcc, s14, v2
	s_cbranch_vccz .LBB0_1047
	v_mov_b32_e32 v2, s26
	s_nop 0
	ds_read_b32 v2, v2
	s_waitcnt lgkmcnt(0)
	v_cmp_gt_u32_e32 vcc, s14, v2
	s_cbranch_vccz .LBB0_1047
	s_add_i32 s24, s24, -5
	s_cmp_eq_u32 s24, 0
	s_cselect_b64 s[50:51], -1, 0
	s_nop 0
	s_branch .LBB0_1047

; #define LAS __attribute__((address_space(3)))
; __device__ __forceinline__ void group_sync(LAS unsigned* cnt, unsigned target, int lane) {
;     asm volatile("s_waitcnt lgkmcnt(0)" ::: "memory");
;     if (lane == 0) __hip_atomic_fetch_add(cnt, 1u, __ATOMIC_RELAXED, __HIP_MEMORY_SCOPE_WORKGROUP);
;     unsigned spins = 0;
;     while (__hip_atomic_load(cnt, __ATOMIC_RELAXED, __HIP_MEMORY_SCOPE_WORKGROUP) < target) { __builtin_amdgcn_s_sleep(1); if (++spins > (1u << 22)) break; }
;     asm volatile("" ::: "memory");
; }
.LBB0_1063:
	v_mov_b32_e32 v4, s26
	ds_read_b32 v4, v4
	s_mov_b64 s[52:53], -1
	s_waitcnt lgkmcnt(0)
	v_cmp_le_u32_e32 vcc, s5, v4
	s_cbranch_vccnz .LBB0_1062
	v_mov_b32_e32 v4, s26
	s_nop 0
	ds_read_b32 v4, v4
	s_waitcnt lgkmcnt(0)
	v_cmp_gt_u32_e32 vcc, s5, v4
	s_cbranch_vccz .LBB0_1062
	v_mov_b32_e32 v4, s26
	s_nop 0
	ds_read_b32 v4, v4
	s_waitcnt lgkmcnt(0)
	v_cmp_gt_u32_e32 vcc, s5, v4
	s_cbranch_vccz .LBB0_1062
	v_mov_b32_e32 v4, s26
	s_nop 0
	ds_read_b32 v4, v4
	s_waitcnt lgkmcnt(0)
	v_cmp_gt_u32_e32 vcc, s5, v4
	s_cbranch_vccz .LBB0_1062
	v_mov_b32_e32 v4, s26
	s_nop 0
	ds_read_b32 v4, v4
	s_waitcnt lgkmcnt(0)
	v_cmp_gt_u32_e32 vcc, s5, v4
	s_cbranch_vccz .LBB0_1062
	s_add_i32 s24, s24, -5
	s_cmp_eq_u32 s24, 0
	s_cselect_b64 s[52:53], -1, 0
	s_nop 0
	s_branch .LBB0_1062
